# v4 + GEMM3 epilogue: row-stat loads cut 4x (one quarter per lane, permlane16/32 all-reduce), single batch
# speedup vs baseline: 1.0140x; 1.0140x over previous
.LBB0_555:
	s_lshl_b32 s9, s8, 8
	s_add_i32 s9, s9, s93
	v_or_b32_e32 v188, s9, v165
	v_or_b32_e32 v184, 16, v188
	v_ashrrev_i32_e32 v189, 31, v188
	v_ashrrev_i32_e32 v185, 31, v184
	v_lshlrev_b64 v[128:129], 6, v[188:189]
	v_lshlrev_b64 v[160:161], 6, v[184:185]
	v_or_b32_e32 v180, 32, v188
	v_lshl_add_u64 v[140:141], s[38:39], 0, v[128:129]
	v_lshl_add_u64 v[166:167], s[38:39], 0, v[160:161]
	v_ashrrev_i32_e32 v181, 31, v180
	v_mbcnt_lo_u32_b32 v193, -1, 0
	v_mbcnt_hi_u32_b32 v193, -1, v193
	v_and_b32_e32 v194, 0x30, v193
	v_mov_b32_e32 v195, 0
	v_lshl_add_u64 v[196:197], v[140:141], 0, v[194:195]
	s_movk_i32 s100, 0x2000
	s_mov_b32 s101, 0
	v_lshl_add_u64 v[198:199], v[196:197], 0, s[100:101]
	global_load_dwordx4 v[200:203], v[196:197], off
	global_load_dwordx4 v[204:207], v[196:197], off offset:1024
	global_load_dwordx4 v[208:211], v[196:197], off offset:2048
	global_load_dwordx4 v[212:215], v[196:197], off offset:3072
	global_load_dwordx4 v[216:219], v[198:199], off
	global_load_dwordx4 v[220:223], v[198:199], off offset:1024
	global_load_dwordx4 v[224:227], v[198:199], off offset:2048
	global_load_dwordx4 v[228:231], v[198:199], off offset:3072
	v_or_b32_e32 v174, 48, v188
	v_ashrrev_i32_e32 v175, 31, v174
	v_add_u32_e32 v170, 0x80, v188
	v_ashrrev_i32_e32 v171, 31, v170
	v_add_u32_e32 v166, 0x90, v188
	v_ashrrev_i32_e32 v167, 31, v166
	v_add_u32_e32 v162, 0xa0, v188
	v_ashrrev_i32_e32 v163, 31, v162
	v_add_u32_e32 v160, 0xb0, v188
	v_ashrrev_i32_e32 v161, 31, v160
	s_cmp_lg_u32 s10, 0
	s_cselect_b64 s[64:65], -1, 0
	s_and_b64 vcc, exec, s[64:65]
	s_waitcnt vmcnt(0)
	v_add_f32_e32 v200, v200, v201
	v_add_f32_e32 v202, v202, v203
	v_add_f32_e32 v204, v204, v205
	v_add_f32_e32 v206, v206, v207
	v_add_f32_e32 v208, v208, v209
	v_add_f32_e32 v210, v210, v211
	v_add_f32_e32 v212, v212, v213
	v_add_f32_e32 v214, v214, v215
	v_add_f32_e32 v216, v216, v217
	v_add_f32_e32 v218, v218, v219
	v_add_f32_e32 v220, v220, v221
	v_add_f32_e32 v222, v222, v223
	v_add_f32_e32 v224, v224, v225
	v_add_f32_e32 v226, v226, v227
	v_add_f32_e32 v228, v228, v229
	v_add_f32_e32 v230, v230, v231
	v_add_f32_e32 v200, v200, v202
	v_add_f32_e32 v204, v204, v206
	v_add_f32_e32 v208, v208, v210
	v_add_f32_e32 v212, v212, v214
	v_add_f32_e32 v216, v216, v218
	v_add_f32_e32 v220, v220, v222
	v_add_f32_e32 v224, v224, v226
	v_add_f32_e32 v228, v228, v230
	v_mov_b32_e32 v201, v200
	v_mov_b32_e32 v205, v204
	v_mov_b32_e32 v209, v208
	v_mov_b32_e32 v213, v212
	v_mov_b32_e32 v217, v216
	v_mov_b32_e32 v221, v220
	v_mov_b32_e32 v225, v224
	v_mov_b32_e32 v229, v228
	s_nop 1
	v_permlane16_swap_b32_e32 v200, v201
	v_permlane16_swap_b32_e32 v204, v205
	v_permlane16_swap_b32_e32 v208, v209
	v_permlane16_swap_b32_e32 v212, v213
	v_permlane16_swap_b32_e32 v216, v217
	v_permlane16_swap_b32_e32 v220, v221
	v_permlane16_swap_b32_e32 v224, v225
	v_permlane16_swap_b32_e32 v228, v229
	v_add_f32_e32 v200, v200, v201
	v_add_f32_e32 v204, v204, v205
	v_add_f32_e32 v208, v208, v209
	v_add_f32_e32 v212, v212, v213
	v_add_f32_e32 v216, v216, v217
	v_add_f32_e32 v220, v220, v221
	v_add_f32_e32 v224, v224, v225
	v_add_f32_e32 v228, v228, v229
	v_mov_b32_e32 v201, v200
	v_mov_b32_e32 v205, v204
	v_mov_b32_e32 v209, v208
	v_mov_b32_e32 v213, v212
	v_mov_b32_e32 v217, v216
	v_mov_b32_e32 v221, v220
	v_mov_b32_e32 v225, v224
	v_mov_b32_e32 v229, v228
	s_nop 1
	v_permlane32_swap_b32_e32 v200, v201
	v_permlane32_swap_b32_e32 v204, v205
	v_permlane32_swap_b32_e32 v208, v209
	v_permlane32_swap_b32_e32 v212, v213
	v_permlane32_swap_b32_e32 v216, v217
	v_permlane32_swap_b32_e32 v220, v221
	v_permlane32_swap_b32_e32 v224, v225
	v_permlane32_swap_b32_e32 v228, v229
	v_add_f32_e32 v200, v200, v201
	v_add_f32_e32 v204, v204, v205
	v_add_f32_e32 v208, v208, v209
	v_add_f32_e32 v212, v212, v213
	v_add_f32_e32 v216, v216, v217
	v_add_f32_e32 v220, v220, v221
	v_add_f32_e32 v224, v224, v225
	v_add_f32_e32 v228, v228, v229
	v_fmamk_f32 v200, v200, 0x3a800000, v187
	v_fmamk_f32 v204, v204, 0x3a800000, v187
	v_fmamk_f32 v208, v208, 0x3a800000, v187
	v_fmamk_f32 v212, v212, 0x3a800000, v187
	v_fmamk_f32 v216, v216, 0x3a800000, v187
	v_fmamk_f32 v220, v220, 0x3a800000, v187
	v_fmamk_f32 v224, v224, 0x3a800000, v187
	v_fmamk_f32 v228, v228, 0x3a800000, v187
	v_rsq_f32_e32 v128, v200
	v_rsq_f32_e32 v190, v204
	v_rsq_f32_e32 v186, v208
	v_rsq_f32_e32 v182, v212
	v_rsq_f32_e32 v178, v216
	v_rsq_f32_e32 v172, v220
	v_rsq_f32_e32 v168, v224
	v_rsq_f32_e32 v164, v228
	s_nop 0
	s_cbranch_vccz .LBB0_698
	s_mov_b64 s[72:73], -1
	s_mov_b64 s[66:67], 0
	s_cmp_lt_i32 s10, 2
	s_mov_b64 s[68:69], 0
	s_cbranch_scc0 .LBB0_699
	s_and_b64 vcc, exec, s[72:73]
	s_cbranch_vccnz .LBB0_705
